# nt hint on the P0 adaLN weight loads and the P10 x1b residual loads (each read once), on top of the other streaming-load nt hints
# baseline (speedup 1.0000x reference)
.LBB0_57:
	v_lshl_add_u64 v[154:155], v[144:145], 0, s[8:9]
	v_add_co_u32_e32 v164, vcc, s14, v154
	ds_read_b128 v[12:15], v158
	ds_read_b128 v[4:7], v158 offset:16
	ds_read_b128 v[0:3], v158 offset:4096
	ds_read_b128 v[8:11], v158 offset:4112
	ds_read_b128 v[48:51], v158 offset:8192
	ds_read_b128 v[40:43], v158 offset:8208
	ds_read_b128 v[20:23], v158 offset:12288
	ds_read_b128 v[16:19], v158 offset:12304
	ds_read_b128 v[52:55], v158 offset:16384
	ds_read_b128 v[44:47], v158 offset:16400
	ds_read_b128 v[28:31], v158 offset:20480
	ds_read_b128 v[24:27], v158 offset:20496
	ds_read_b128 v[64:67], v158 offset:24576
	ds_read_b128 v[56:59], v158 offset:24592
	ds_read_b128 v[36:39], v158 offset:28672
	ds_read_b128 v[32:35], v158 offset:28688
	v_addc_co_u32_e32 v165, vcc, 0, v155, vcc
	v_add_co_u32_e32 v166, vcc, s15, v154
	ds_read_b128 v[68:71], v158 offset:32768
	ds_read_b128 v[60:63], v158 offset:32784
	ds_read_b128 v[80:83], v158 offset:32
	ds_read_b128 v[76:79], v158 offset:48
	ds_read_b128 v[72:75], v158 offset:4128
	ds_read_b128 v[84:87], v158 offset:4144
	ds_read_b128 v[116:119], v158 offset:8224
	ds_read_b128 v[112:115], v158 offset:8240
	ds_read_b128 v[92:95], v158 offset:12320
	ds_read_b128 v[88:91], v158 offset:12336
	ds_read_b128 v[128:131], v158 offset:16416
	ds_read_b128 v[120:123], v158 offset:16432
	ds_read_b128 v[100:103], v158 offset:20512
	ds_read_b128 v[96:99], v158 offset:20528
	ds_read_b128 v[132:135], v158 offset:24608
	ds_read_b128 v[124:127], v158 offset:24624
	ds_read_b128 v[108:111], v158 offset:28704
	ds_read_b128 v[104:107], v158 offset:28720
	ds_read_b128 v[160:163], v158 offset:32800
	ds_read_b128 v[136:139], v158 offset:32816
	v_addc_co_u32_e32 v167, vcc, 0, v155, vcc
	v_add_co_u32_e32 v168, vcc, s33, v154
	s_waitcnt lgkmcnt(14)
	v_mov_b32_e32 v194, v12
	v_addc_co_u32_e32 v169, vcc, 0, v155, vcc
	v_add_co_u32_e32 v170, vcc, s82, v154
	v_mov_b32_e32 v195, v0
	s_nop 0
	v_addc_co_u32_e32 v171, vcc, 0, v155, vcc
	v_add_co_u32_e32 v172, vcc, s83, v154
	v_mov_b32_e32 v0, v13
	s_nop 0
	v_addc_co_u32_e32 v173, vcc, 0, v155, vcc
	v_add_co_u32_e32 v174, vcc, s84, v154
	v_mov_b32_e32 v12, v14
	s_nop 0
	v_addc_co_u32_e32 v175, vcc, 0, v155, vcc
	v_add_co_u32_e32 v176, vcc, s85, v154
	v_mov_b32_e32 v13, v2
	s_nop 0
	v_addc_co_u32_e32 v177, vcc, 0, v155, vcc
	v_add_co_u32_e32 v178, vcc, s86, v154
	v_mov_b32_e32 v2, v15
	s_nop 0
	v_addc_co_u32_e32 v179, vcc, 0, v155, vcc
	v_add_co_u32_e32 v180, vcc, s87, v154
	v_mov_b32_e32 v14, v48
	s_nop 0
	v_addc_co_u32_e32 v181, vcc, 0, v155, vcc
	v_add_co_u32_e32 v182, vcc, s88, v154
	v_mov_b32_e32 v15, v20
	s_nop 0
	v_addc_co_u32_e32 v183, vcc, 0, v155, vcc
	v_add_co_u32_e32 v184, vcc, s89, v154
	v_mov_b32_e32 v20, v49
	s_nop 0
	v_addc_co_u32_e32 v185, vcc, 0, v155, vcc
	v_add_co_u32_e32 v186, vcc, s90, v154
	v_mov_b32_e32 v48, v50
	s_nop 0
	v_addc_co_u32_e32 v187, vcc, 0, v155, vcc
	v_add_co_u32_e32 v188, vcc, s91, v154
	v_mov_b32_e32 v49, v22
	s_nop 0
	v_addc_co_u32_e32 v189, vcc, 0, v155, vcc
	v_add_co_u32_e32 v190, vcc, s92, v154
	v_mov_b32_e32 v22, v51
	s_nop 0
	v_addc_co_u32_e32 v191, vcc, 0, v155, vcc
	v_add_co_u32_e32 v192, vcc, s93, v154
	v_mov_b32_e32 v50, v52
	s_nop 0
	v_addc_co_u32_e32 v193, vcc, 0, v155, vcc
	global_load_dword v164, v[164:165], off nt
	s_nop 0
	global_load_dword v166, v[166:167], off nt
	s_nop 0
	global_load_dword v168, v[168:169], off nt
	s_nop 0
	global_load_dword v170, v[170:171], off nt
	s_nop 0
	global_load_dword v172, v[172:173], off nt
	s_nop 0
	global_load_dword v174, v[174:175], off nt
	s_nop 0
	global_load_dword v176, v[176:177], off nt
	s_nop 0
	global_load_dword v154, v[154:155], off nt
	s_nop 0
	global_load_dword v178, v[178:179], off nt
	s_nop 0
	global_load_dword v180, v[180:181], off nt
	s_nop 0
	global_load_dword v182, v[182:183], off nt
	s_nop 0
	global_load_dword v184, v[184:185], off nt
	s_nop 0
	global_load_dword v186, v[186:187], off nt
	s_nop 0
	global_load_dword v188, v[188:189], off nt
	s_nop 0
	global_load_dword v190, v[190:191], off nt
	s_nop 0
	global_load_dword v192, v[192:193], off nt
	v_mov_b32_e32 v51, v28
	v_mov_b32_e32 v28, v53
	v_mov_b32_e32 v52, v54
	v_mov_b32_e32 v53, v30
	v_mov_b32_e32 v30, v55
	v_mov_b32_e32 v54, v64
	v_mov_b32_e32 v55, v36
	v_mov_b32_e32 v36, v65
	v_mov_b32_e32 v64, v66
	v_mov_b32_e32 v65, v38
	v_mov_b32_e32 v38, v67
	v_mov_b32_e32 v66, v4
	v_mov_b32_e32 v67, v8
	v_mov_b32_e32 v8, v5
	v_mov_b32_e32 v4, v6
	v_mov_b32_e32 v5, v10
	v_mov_b32_e32 v10, v7
	v_mov_b32_e32 v6, v40
	v_mov_b32_e32 v7, v16
	v_mov_b32_e32 v16, v41
	v_mov_b32_e32 v40, v42
	v_mov_b32_e32 v41, v18
	v_mov_b32_e32 v18, v43
	v_mov_b32_e32 v42, v44
	v_mov_b32_e32 v43, v24
	v_mov_b32_e32 v24, v45
	v_mov_b32_e32 v44, v46
	v_mov_b32_e32 v45, v26
	v_mov_b32_e32 v26, v47
	v_mov_b32_e32 v46, v56
	v_mov_b32_e32 v47, v32
	v_mov_b32_e32 v32, v57
	v_mov_b32_e32 v56, v58
	v_mov_b32_e32 v57, v34
	v_mov_b32_e32 v34, v59
	v_mov_b32_e32 v58, v80
	v_mov_b32_e32 v59, v72
	v_mov_b32_e32 v72, v81
	v_mov_b32_e32 v80, v82
	v_mov_b32_e32 v81, v74
	v_mov_b32_e32 v74, v83
	s_waitcnt lgkmcnt(13)
	v_mov_b32_e32 v82, v116
	s_waitcnt lgkmcnt(11)
	v_mov_b32_e32 v83, v92
	v_mov_b32_e32 v92, v117
	v_mov_b32_e32 v116, v118
	v_mov_b32_e32 v117, v94
	v_mov_b32_e32 v94, v119
	s_waitcnt lgkmcnt(9)
	v_mov_b32_e32 v118, v128
	s_waitcnt lgkmcnt(7)
	v_mov_b32_e32 v119, v100
	v_mov_b32_e32 v100, v129
	v_mov_b32_e32 v128, v130
	v_mov_b32_e32 v129, v102
	v_mov_b32_e32 v102, v131
	s_waitcnt lgkmcnt(5)
	v_mov_b32_e32 v130, v132
	s_waitcnt lgkmcnt(3)
	v_mov_b32_e32 v131, v108
	v_mov_b32_e32 v108, v133
	v_mov_b32_e32 v132, v134
	v_mov_b32_e32 v133, v110
	v_mov_b32_e32 v110, v135
	v_mov_b32_e32 v134, v76
	v_mov_b32_e32 v135, v84
	v_mov_b32_e32 v84, v77
	v_mov_b32_e32 v76, v78
	v_mov_b32_e32 v77, v86
	v_mov_b32_e32 v86, v79
	v_mov_b32_e32 v78, v112
	v_mov_b32_e32 v79, v88
	v_mov_b32_e32 v88, v113
	v_mov_b32_e32 v112, v114
	v_mov_b32_e32 v113, v90
	v_mov_b32_e32 v90, v115
	v_mov_b32_e32 v114, v120
	v_mov_b32_e32 v115, v96
	v_mov_b32_e32 v96, v121
	v_mov_b32_e32 v120, v122
	v_mov_b32_e32 v121, v98
	v_mov_b32_e32 v98, v123
	v_mov_b32_e32 v122, v124
	s_waitcnt lgkmcnt(2)
	v_mov_b32_e32 v123, v104
	v_mov_b32_e32 v104, v125
	v_mov_b32_e32 v124, v126
	v_mov_b32_e32 v125, v106
	v_mov_b32_e32 v106, v127
	s_waitcnt vmcnt(8)
	v_pk_fma_f32 v[126:127], v[154:155], v[194:195], v[146:147] op_sel_hi:[0,1,1]
	v_pk_fma_f32 v[14:15], v[154:155], v[14:15], v[148:149] op_sel_hi:[0,1,1]
	v_pk_fma_f32 v[50:51], v[154:155], v[50:51], v[150:151] op_sel_hi:[0,1,1]
	v_pk_fma_f32 v[54:55], v[154:155], v[54:55], v[152:153] op_sel_hi:[0,1,1]
	v_fmac_f32_e32 v159, v154, v68
	v_pk_fma_f32 v[0:1], v[164:165], v[0:1], v[126:127] op_sel_hi:[0,1,1]
	v_pk_fma_f32 v[14:15], v[164:165], v[20:21], v[14:15] op_sel_hi:[0,1,1]
	v_pk_fma_f32 v[20:21], v[164:165], v[28:29], v[50:51] op_sel_hi:[0,1,1]
	v_pk_fma_f32 v[28:29], v[164:165], v[36:37], v[54:55] op_sel_hi:[0,1,1]
	v_fmac_f32_e32 v159, v164, v69
	v_pk_fma_f32 v[0:1], v[166:167], v[12:13], v[0:1] op_sel_hi:[0,1,1]
	v_pk_fma_f32 v[12:13], v[166:167], v[48:49], v[14:15] op_sel_hi:[0,1,1]
	v_pk_fma_f32 v[14:15], v[166:167], v[52:53], v[20:21] op_sel_hi:[0,1,1]
	v_pk_fma_f32 v[20:21], v[166:167], v[64:65], v[28:29] op_sel_hi:[0,1,1]
	v_fmac_f32_e32 v159, v166, v70
	v_pk_fma_f32 v[0:1], v[168:169], v[2:3], v[0:1] op_sel_hi:[0,1,1]
	v_pk_fma_f32 v[2:3], v[168:169], v[22:23], v[12:13] op_sel_hi:[0,1,1]
	v_pk_fma_f32 v[12:13], v[168:169], v[30:31], v[14:15] op_sel_hi:[0,1,1]
	v_pk_fma_f32 v[14:15], v[168:169], v[38:39], v[20:21] op_sel_hi:[0,1,1]
	v_fmac_f32_e32 v159, v168, v71
	v_pk_fma_f32 v[0:1], v[170:171], v[66:67], v[0:1] op_sel_hi:[0,1,1]
	v_pk_fma_f32 v[2:3], v[170:171], v[6:7], v[2:3] op_sel_hi:[0,1,1]
	v_pk_fma_f32 v[6:7], v[170:171], v[42:43], v[12:13] op_sel_hi:[0,1,1]
	v_pk_fma_f32 v[12:13], v[170:171], v[46:47], v[14:15] op_sel_hi:[0,1,1]
	v_fmac_f32_e32 v159, v170, v60
	v_pk_fma_f32 v[0:1], v[172:173], v[8:9], v[0:1] op_sel_hi:[0,1,1]
	v_pk_fma_f32 v[2:3], v[172:173], v[16:17], v[2:3] op_sel_hi:[0,1,1]
	v_pk_fma_f32 v[6:7], v[172:173], v[24:25], v[6:7] op_sel_hi:[0,1,1]
	v_pk_fma_f32 v[8:9], v[172:173], v[32:33], v[12:13] op_sel_hi:[0,1,1]
	v_fmac_f32_e32 v159, v172, v61
	v_pk_fma_f32 v[0:1], v[174:175], v[4:5], v[0:1] op_sel_hi:[0,1,1]
	v_pk_fma_f32 v[2:3], v[174:175], v[40:41], v[2:3] op_sel_hi:[0,1,1]
	v_pk_fma_f32 v[4:5], v[174:175], v[44:45], v[6:7] op_sel_hi:[0,1,1]
	v_pk_fma_f32 v[6:7], v[174:175], v[56:57], v[8:9] op_sel_hi:[0,1,1]
	v_fmac_f32_e32 v159, v174, v62
	v_pk_fma_f32 v[0:1], v[176:177], v[10:11], v[0:1] op_sel_hi:[0,1,1]
	v_pk_fma_f32 v[2:3], v[176:177], v[18:19], v[2:3] op_sel_hi:[0,1,1]
	v_pk_fma_f32 v[4:5], v[176:177], v[26:27], v[4:5] op_sel_hi:[0,1,1]
	v_pk_fma_f32 v[6:7], v[176:177], v[34:35], v[6:7] op_sel_hi:[0,1,1]
	v_fmac_f32_e32 v159, v176, v63
	s_waitcnt vmcnt(7)
	v_pk_fma_f32 v[0:1], v[178:179], v[58:59], v[0:1] op_sel_hi:[0,1,1]
	v_pk_fma_f32 v[2:3], v[178:179], v[82:83], v[2:3] op_sel_hi:[0,1,1]
	v_pk_fma_f32 v[4:5], v[178:179], v[118:119], v[4:5] op_sel_hi:[0,1,1]
	v_pk_fma_f32 v[6:7], v[178:179], v[130:131], v[6:7] op_sel_hi:[0,1,1]
	s_waitcnt lgkmcnt(1)
	v_fmac_f32_e32 v159, v178, v160
	s_waitcnt vmcnt(6)
	v_pk_fma_f32 v[0:1], v[180:181], v[72:73], v[0:1] op_sel_hi:[0,1,1]
	v_pk_fma_f32 v[2:3], v[180:181], v[92:93], v[2:3] op_sel_hi:[0,1,1]
	v_pk_fma_f32 v[4:5], v[180:181], v[100:101], v[4:5] op_sel_hi:[0,1,1]
	v_pk_fma_f32 v[6:7], v[180:181], v[108:109], v[6:7] op_sel_hi:[0,1,1]
	v_fmac_f32_e32 v159, v180, v161
	s_waitcnt vmcnt(5)
	v_pk_fma_f32 v[0:1], v[182:183], v[80:81], v[0:1] op_sel_hi:[0,1,1]
	v_pk_fma_f32 v[2:3], v[182:183], v[116:117], v[2:3] op_sel_hi:[0,1,1]
	v_pk_fma_f32 v[4:5], v[182:183], v[128:129], v[4:5] op_sel_hi:[0,1,1]
	v_pk_fma_f32 v[6:7], v[182:183], v[132:133], v[6:7] op_sel_hi:[0,1,1]
	v_fmac_f32_e32 v159, v182, v162
	s_waitcnt vmcnt(4)
	v_pk_fma_f32 v[0:1], v[184:185], v[74:75], v[0:1] op_sel_hi:[0,1,1]
	v_pk_fma_f32 v[2:3], v[184:185], v[94:95], v[2:3] op_sel_hi:[0,1,1]
	v_pk_fma_f32 v[4:5], v[184:185], v[102:103], v[4:5] op_sel_hi:[0,1,1]
	v_pk_fma_f32 v[6:7], v[184:185], v[110:111], v[6:7] op_sel_hi:[0,1,1]
	v_fmac_f32_e32 v159, v184, v163
	s_waitcnt vmcnt(3)
	v_pk_fma_f32 v[0:1], v[186:187], v[134:135], v[0:1] op_sel_hi:[0,1,1]
	v_pk_fma_f32 v[2:3], v[186:187], v[78:79], v[2:3] op_sel_hi:[0,1,1]
	v_pk_fma_f32 v[4:5], v[186:187], v[114:115], v[4:5] op_sel_hi:[0,1,1]
	v_pk_fma_f32 v[6:7], v[186:187], v[122:123], v[6:7] op_sel_hi:[0,1,1]
	s_waitcnt lgkmcnt(0)
	v_fmac_f32_e32 v159, v186, v136
	s_add_u32 s8, s8, 0x30000
	s_waitcnt vmcnt(2)
	v_pk_fma_f32 v[0:1], v[188:189], v[84:85], v[0:1] op_sel_hi:[0,1,1]
	v_pk_fma_f32 v[2:3], v[188:189], v[88:89], v[2:3] op_sel_hi:[0,1,1]
	v_pk_fma_f32 v[4:5], v[188:189], v[96:97], v[4:5] op_sel_hi:[0,1,1]
	v_pk_fma_f32 v[6:7], v[188:189], v[104:105], v[6:7] op_sel_hi:[0,1,1]
	v_fmac_f32_e32 v159, v188, v137
	s_addc_u32 s9, s9, 0
	s_waitcnt vmcnt(1)
	v_pk_fma_f32 v[0:1], v[190:191], v[76:77], v[0:1] op_sel_hi:[0,1,1]
	v_pk_fma_f32 v[2:3], v[190:191], v[112:113], v[2:3] op_sel_hi:[0,1,1]
	v_pk_fma_f32 v[4:5], v[190:191], v[120:121], v[4:5] op_sel_hi:[0,1,1]
	v_pk_fma_f32 v[6:7], v[190:191], v[124:125], v[6:7] op_sel_hi:[0,1,1]
	v_fmac_f32_e32 v159, v190, v138
	v_add_u32_e32 v158, 64, v158
	s_cmp_eq_u32 s8, 0xc0000
	s_waitcnt vmcnt(0)
	v_pk_fma_f32 v[146:147], v[192:193], v[86:87], v[0:1] op_sel_hi:[0,1,1]
	v_pk_fma_f32 v[148:149], v[192:193], v[90:91], v[2:3] op_sel_hi:[0,1,1]
	v_pk_fma_f32 v[150:151], v[192:193], v[98:99], v[4:5] op_sel_hi:[0,1,1]
	v_pk_fma_f32 v[152:153], v[192:193], v[106:107], v[6:7] op_sel_hi:[0,1,1]
	v_fmac_f32_e32 v159, v192, v139
	s_cbranch_scc0 .LBB0_57
	v_lshl_add_u32 v0, v140, 2, 0
	v_mad_u64_u32 v[2:3], s[8:9], v143, s94, v[0:1]
	v_add_u32_e32 v1, 0x9000, v2
	v_cmp_gt_i32_e32 vcc, s95, v142
	ds_write2_b32 v1, v146, v147 offset1:32
	ds_write2_b32 v1, v148, v149 offset0:64 offset1:96
	ds_write2_b32 v1, v150, v151 offset0:128 offset1:160
	ds_write2_b32 v1, v152, v153 offset0:192 offset1:224
	ds_write_b32 v2, v159 offset:37888
	s_waitcnt lgkmcnt(0)
	s_barrier
	s_and_saveexec_b64 s[8:9], vcc
	s_cbranch_execz .LBB0_52
	s_mul_i32 s7, s10, 0xc00
	s_add_i32 s7, s7, s6
	v_or_b32_e32 v2, s7, v140
	v_ashrrev_i32_e32 v3, 31, v2
	v_lshl_add_u64 v[2:3], v[2:3], 2, s[62:63]
	global_load_dword v1, v[2:3], off
	v_lshl_add_u32 v16, v143, 7, v0
	ds_read_b32 v0, v16 offset:36864
	ds_read_b32 v2, v16 offset:38016
	ds_read_b32 v3, v16 offset:39168
	ds_read_b32 v4, v16 offset:40320
	ds_read_b32 v5, v16 offset:41472
	ds_read_b32 v6, v16 offset:42624
	ds_read_b32 v7, v16 offset:43776
	ds_read_b32 v8, v16 offset:44928
	ds_read_b32 v9, v16 offset:46080
	ds_read_b32 v10, v16 offset:47232
	ds_read_b32 v11, v16 offset:48384
	ds_read_b32 v12, v16 offset:49536
	ds_read_b32 v13, v16 offset:50688
	ds_read_b32 v14, v16 offset:51840
	ds_read_b32 v15, v16 offset:52992
	ds_read_b32 v16, v16 offset:54144
	s_add_i32 s7, s97, 0x5f
	s_cmpk_lt_u32 s7, 0xbf
	s_cselect_b64 s[12:13], -1, 0
	s_and_b64 vcc, exec, s[12:13]
	s_cbranch_vccnz .LBB0_61
	v_cmp_gt_i32_e32 vcc, 8, v143
	s_andn2_b64 s[12:13], s[12:13], exec
	s_and_b64 vcc, vcc, exec
	s_mov_b64 s[10:11], 0x151b000
	s_or_b64 s[12:13], s[12:13], vcc
	s_and_b64 exec, exec, s[12:13]
	s_cbranch_execz .LBB0_52
	s_branch .LBB0_51

.LBB0_1889:
	s_add_i32 s1, s0, 1
	s_bitcmp1_b32 s0, 0
	s_cselect_b32 s0, 0x12000, 0
	s_add_i32 s0, s0, 0
	v_add_u32_e32 v172, s0, v188
	v_add_u32_e32 v226, s0, v193
	ds_read_b64_tr_b16 v[198:199], v172 offset:64
	ds_read_b64_tr_b16 v[202:203], v172 offset:128
	ds_read_b64_tr_b16 v[206:207], v172 offset:192
	ds_read_b64_tr_b16 v[200:201], v172 offset:2368
	ds_read_b64_tr_b16 v[204:205], v172 offset:2432
	ds_read_b64_tr_b16 v[208:209], v172 offset:2496
	ds_read_b128 v[214:217], v226 offset:36896
	ds_read_b128 v[222:225], v226 offset:41504
	v_lshl_add_u64 v[136:137], s[78:79], 0, v[182:183]
	v_add_co_u32_e32 v128, vcc, s63, v136
	v_lshl_add_u64 v[152:153], s[78:79], 0, v[180:181]
	s_nop 0
	v_addc_co_u32_e32 v129, vcc, 0, v137, vcc
	v_add_co_u32_e32 v132, vcc, s64, v136
	s_nop 0
	s_nop 0
	v_addc_co_u32_e32 v133, vcc, 0, v137, vcc
	v_add_co_u32_e32 v138, vcc, s65, v136
	global_load_dwordx4 v[128:131], v[128:129], off
	s_nop 0
	global_load_dwordx4 v[132:135], v[132:133], off
	v_addc_co_u32_e32 v139, vcc, 0, v137, vcc
	v_add_co_u32_e32 v140, vcc, s66, v136
	s_nop 1
	v_addc_co_u32_e32 v141, vcc, 0, v137, vcc
	v_add_co_u32_e32 v144, vcc, s67, v152
	global_load_dwordx4 v[136:139], v[138:139], off
	s_nop 0
	global_load_dwordx4 v[140:143], v[140:141], off
	v_addc_co_u32_e32 v145, vcc, 0, v153, vcc
	v_add_co_u32_e32 v148, vcc, s68, v152
	s_nop 1
	v_addc_co_u32_e32 v149, vcc, 0, v153, vcc
	v_add_co_u32_e32 v154, vcc, s69, v152
	global_load_dwordx4 v[144:147], v[144:145], off offset:128
	s_nop 0
	global_load_dwordx4 v[148:151], v[148:149], off offset:128
	v_addc_co_u32_e32 v155, vcc, 0, v153, vcc
	v_add_co_u32_e32 v156, vcc, s70, v152
	s_nop 1
	v_addc_co_u32_e32 v157, vcc, 0, v153, vcc
	global_load_dwordx4 v[152:155], v[154:155], off offset:128
	s_nop 0
	global_load_dwordx4 v[156:159], v[156:157], off offset:128
	s_waitcnt lgkmcnt(8)
	v_mfma_f32_32x32x16_bf16 v[96:111], v[194:197], v[210:213], v[96:111]
	s_bitcmp1_b32 s1, 0
	s_cselect_b32 s18, 0x12000, 0
	s_add_i32 s18, s18, 0
	v_add_u32_e32 v234, s18, v188
	v_add_u32_e32 v235, s18, v193
	v_lshl_add_u64 v[180:181], v[180:181], 0, s[8:9]
	v_lshl_add_u64 v[182:183], v[182:183], 0, s[10:11]
	s_mov_b32 s0, s1
	s_cmp_eq_u32 s1, 15
	v_mfma_f32_32x32x16_bf16 v[112:127], v[194:197], v[218:221], v[112:127]
	ds_read_b64_tr_b16 v[196:197], v172 offset:11520
	s_waitcnt lgkmcnt(5)
	v_mfma_f32_32x32x16_bf16 v[64:79], v[198:201], v[210:213], v[64:79]
	v_mfma_f32_32x32x16_bf16 v[80:95], v[198:201], v[218:221], v[80:95]
	s_waitcnt lgkmcnt(4)
	v_mfma_f32_32x32x16_bf16 v[32:47], v[202:205], v[210:213], v[32:47]
	v_mfma_f32_32x32x16_bf16 v[48:63], v[202:205], v[218:221], v[48:63]
	s_waitcnt lgkmcnt(3)
	v_mfma_f32_32x32x16_bf16 v[0:15], v[206:209], v[210:213], v[0:15]
	v_mfma_f32_32x32x16_bf16 v[16:31], v[206:209], v[218:221], v[16:31]
	ds_read_b64_tr_b16 v[194:195], v172 offset:9216
	ds_read_b64_tr_b16 v[198:199], v172 offset:9280
	ds_read_b64_tr_b16 v[202:203], v172 offset:9344
	ds_read_b64_tr_b16 v[206:207], v172 offset:9408
	ds_read_b64_tr_b16 v[200:201], v172 offset:11584
	ds_read_b64_tr_b16 v[204:205], v172 offset:11648
	ds_read_b64_tr_b16 v[208:209], v172 offset:11712
	s_waitcnt lgkmcnt(6)
	v_mfma_f32_32x32x16_bf16 v[96:111], v[194:197], v[214:217], v[96:111]
	v_mfma_f32_32x32x16_bf16 v[112:127], v[194:197], v[222:225], v[112:127]
	s_waitcnt lgkmcnt(2)
	v_mfma_f32_32x32x16_bf16 v[64:79], v[198:201], v[214:217], v[64:79]
	v_mfma_f32_32x32x16_bf16 v[80:95], v[198:201], v[222:225], v[80:95]
	ds_read_b64_tr_b16 v[196:197], v172 offset:20736
	ds_read_b64_tr_b16 v[194:195], v172 offset:18432
	ds_read_b64_tr_b16 v[198:199], v172 offset:18496
	s_waitcnt lgkmcnt(4)
	v_mfma_f32_32x32x16_bf16 v[32:47], v[202:205], v[214:217], v[32:47]
	v_mfma_f32_32x32x16_bf16 v[48:63], v[202:205], v[222:225], v[48:63]
	s_waitcnt lgkmcnt(3)
	v_mfma_f32_32x32x16_bf16 v[0:15], v[206:209], v[214:217], v[0:15]
	v_mfma_f32_32x32x16_bf16 v[16:31], v[206:209], v[222:225], v[16:31]
	ds_read_b64_tr_b16 v[202:203], v172 offset:18560
	ds_read_b64_tr_b16 v[206:207], v172 offset:18624
	ds_read_b128 v[210:213], v226 offset:36928
	ds_read_b64_tr_b16 v[200:201], v172 offset:20800
	ds_read_b64_tr_b16 v[204:205], v172 offset:20864
	ds_read_b64_tr_b16 v[208:209], v172 offset:20928
	ds_read_b128 v[214:217], v226 offset:36960
	ds_read_b128 v[218:221], v226 offset:41536
	ds_read_b128 v[222:225], v226 offset:41568
	s_waitcnt lgkmcnt(6)
	v_mfma_f32_32x32x16_bf16 v[96:111], v[194:197], v[210:213], v[96:111]
	s_waitcnt lgkmcnt(1)
	v_mfma_f32_32x32x16_bf16 v[112:127], v[194:197], v[218:221], v[112:127]
	ds_read_b64_tr_b16 v[196:197], v172 offset:29952
	v_mfma_f32_32x32x16_bf16 v[64:79], v[198:201], v[210:213], v[64:79]
	v_mfma_f32_32x32x16_bf16 v[80:95], v[198:201], v[218:221], v[80:95]
	v_mfma_f32_32x32x16_bf16 v[32:47], v[202:205], v[210:213], v[32:47]
	v_mfma_f32_32x32x16_bf16 v[48:63], v[202:205], v[218:221], v[48:63]
	v_mfma_f32_32x32x16_bf16 v[0:15], v[206:209], v[210:213], v[0:15]
	v_mfma_f32_32x32x16_bf16 v[16:31], v[206:209], v[218:221], v[16:31]
	ds_read_b64_tr_b16 v[194:195], v172 offset:27648
	ds_read_b64_tr_b16 v[198:199], v172 offset:27712
	ds_read_b64_tr_b16 v[202:203], v172 offset:27776
	ds_read_b64_tr_b16 v[206:207], v172 offset:27840
	ds_read_b64_tr_b16 v[200:201], v172 offset:30016
	ds_read_b64_tr_b16 v[204:205], v172 offset:30080
	ds_read_b64_tr_b16 v[208:209], v172 offset:30144
	v_add_u32_e32 v172, s18, v170
	s_waitcnt vmcnt(7)
	ds_write_b128 v172, v[128:131]
	s_waitcnt vmcnt(6)
	ds_write_b128 v172, v[132:135] offset:9216
	s_waitcnt vmcnt(5)
	ds_write_b128 v172, v[136:139] offset:18432
	s_waitcnt vmcnt(4)
	ds_write_b128 v172, v[140:143] offset:27648
	s_waitcnt lgkmcnt(10)
	v_mfma_f32_32x32x16_bf16 v[96:111], v[194:197], v[214:217], v[96:111]
	v_mfma_f32_32x32x16_bf16 v[112:127], v[194:197], v[222:225], v[112:127]
	v_add_u32_e32 v194, s18, v176
	s_waitcnt vmcnt(3)
	ds_write_b128 v194, v[144:147] offset:36864
	s_waitcnt vmcnt(2)
	ds_write_b128 v194, v[148:151] offset:46080
	s_waitcnt vmcnt(1)
	ds_write_b128 v194, v[152:155] offset:55296
	s_waitcnt vmcnt(0)
	ds_write_b128 v194, v[156:159] offset:64512
	s_waitcnt lgkmcnt(0)
	s_barrier
	ds_read_b64_tr_b16 v[196:197], v234 offset:2304
	ds_read_b64_tr_b16 v[194:195], v234
	ds_read_b128 v[210:213], v235 offset:36864
	ds_read_b128 v[218:221], v235 offset:41472
	v_mfma_f32_32x32x16_bf16 v[64:79], v[198:201], v[214:217], v[64:79]
	v_mfma_f32_32x32x16_bf16 v[80:95], v[198:201], v[222:225], v[80:95]
	v_mfma_f32_32x32x16_bf16 v[32:47], v[202:205], v[214:217], v[32:47]
	v_mfma_f32_32x32x16_bf16 v[48:63], v[202:205], v[222:225], v[48:63]
	v_mfma_f32_32x32x16_bf16 v[0:15], v[206:209], v[214:217], v[0:15]
	v_mfma_f32_32x32x16_bf16 v[16:31], v[206:209], v[222:225], v[16:31]
	s_cbranch_scc0 .LBB0_1889
	v_add_co_u32_e32 v136, vcc, 0x780000, v160
	s_lshl_b32 s0, s16, 8
	s_nop 0
	v_addc_co_u32_e32 v137, vcc, 0, v161, vcc
	v_add_co_u32_e32 v128, vcc, 0x7a0000, v160
	s_nop 1
	v_addc_co_u32_e32 v129, vcc, 0, v161, vcc
	v_add_co_u32_e32 v132, vcc, 0x7c0000, v160
	s_nop 1
	v_addc_co_u32_e32 v133, vcc, 0, v161, vcc
	v_add_co_u32_e32 v144, vcc, 0x7e0000, v160
	global_load_dwordx4 v[128:131], v[128:129], off
	s_nop 0
	global_load_dwordx4 v[132:135], v[132:133], off
	v_addc_co_u32_e32 v145, vcc, 0, v161, vcc
	global_load_dwordx4 v[136:139], v[136:137], off
	s_nop 0
	global_load_dwordx4 v[140:143], v[162:163], off offset:1920
	s_nop 0
	global_load_dwordx4 v[144:147], v[144:145], off
	s_nop 0
	global_load_dwordx4 v[148:151], v[164:165], off offset:1920
	global_load_dwordx4 v[152:155], v[166:167], off offset:1920
	global_load_dwordx4 v[156:159], v[168:169], off offset:1920
	v_add_u32_e32 v160, v190, v192
	v_add_u32_e32 v168, 64, v160
	v_add_u32_e32 v169, 0x80, v160
	v_add_u32_e32 v170, 0xc0, v160
	v_add_u32_e32 v160, v191, v189
	v_add_u32_e32 v172, 0x9000, v160
	v_add_u32_e32 v176, 0xa200, v160
	s_add_i32 s1, 0, 0x12000
	v_add_u32_e32 v162, s1, v188
	v_add_u32_e32 v182, s1, v168
	v_add_u32_e32 v164, s1, v172
	ds_read_b64_tr_b16 v[160:161], v162
	ds_read_b64_tr_b16 v[162:163], v162 offset:2304
	ds_read_b128 v[164:167], v164
	v_add_u32_e32 v189, s1, v176
	ds_read_b64_tr_b16 v[180:181], v182
	ds_read_b64_tr_b16 v[182:183], v182 offset:2304
	ds_read_b128 v[190:193], v189
	s_waitcnt lgkmcnt(3)
	v_mfma_f32_32x32x16_bf16 v[96:111], v[160:163], v[164:167], v[96:111]
	v_add_u32_e32 v189, s1, v170
	v_add_u32_e32 v200, s71, v168
	v_add_u32_e32 v208, s71, v170
	v_add_u32_e32 v214, s72, v176
	s_mulk_i32 s21, 0x2200
	s_add_i32 s21, s1, s21
	s_or_b32 s0, s22, s0
	s_waitcnt lgkmcnt(0)
	v_mfma_f32_32x32x16_bf16 v[112:127], v[160:163], v[190:193], v[112:127]
	v_add_u32_e32 v162, s1, v169
	ds_read_b64_tr_b16 v[160:161], v162
	ds_read_b64_tr_b16 v[162:163], v162 offset:2304
	ds_read_b64_tr_b16 v[194:195], v189
	ds_read_b64_tr_b16 v[196:197], v189 offset:2304
	v_add_u32_e32 v189, s71, v188
	s_add_i32 s1, s20, s14
	v_lshlrev_b32_e32 v175, 2, v175
	v_mfma_f32_32x32x16_bf16 v[64:79], v[180:183], v[164:167], v[64:79]
	v_mfma_f32_32x32x16_bf16 v[80:95], v[180:183], v[190:193], v[80:95]
	ds_read_b64_tr_b16 v[180:181], v189
	ds_read_b64_tr_b16 v[182:183], v189 offset:2304
	ds_read_b64_tr_b16 v[198:199], v200
	ds_read_b64_tr_b16 v[200:201], v200 offset:2304
	v_add_u32_e32 v189, s71, v169
	ds_read_b64_tr_b16 v[202:203], v189
	ds_read_b64_tr_b16 v[204:205], v189 offset:2304
	ds_read_b64_tr_b16 v[206:207], v208
	ds_read_b64_tr_b16 v[208:209], v208 offset:2304
	v_add_u32_e32 v189, s72, v172
	ds_read_b128 v[210:213], v189
	ds_read_b128 v[214:217], v214
	v_add_u32_e32 v189, s73, v188
	s_waitcnt lgkmcnt(12)
	v_mfma_f32_32x32x16_bf16 v[32:47], v[160:163], v[164:167], v[32:47]
	v_mfma_f32_32x32x16_bf16 v[48:63], v[160:163], v[190:193], v[48:63]
	v_add_u32_e32 v160, s73, v168
	ds_read_b64_tr_b16 v[218:219], v189
	ds_read_b64_tr_b16 v[220:221], v189 offset:2304
	ds_read_b64_tr_b16 v[222:223], v160
	ds_read_b64_tr_b16 v[224:225], v160 offset:2304
	v_add_u32_e32 v160, s73, v169
	v_add_u32_e32 v161, s73, v170
	ds_read_b64_tr_b16 v[226:227], v160
	ds_read_b64_tr_b16 v[228:229], v160 offset:2304
	ds_read_b64_tr_b16 v[230:231], v161
	ds_read_b64_tr_b16 v[232:233], v161 offset:2304
	v_add_u32_e32 v160, s80, v172
	v_add_u32_e32 v161, s80, v176
	s_waitcnt lgkmcnt(14)
	v_mfma_f32_32x32x16_bf16 v[0:15], v[194:197], v[164:167], v[0:15]
	ds_read_b128 v[234:237], v160
	ds_read_b128 v[238:241], v161
	v_add_u32_e32 v160, s81, v188
	v_add_u32_e32 v161, s81, v168
	v_add_u32_e32 v162, s81, v170
	v_add_u32_e32 v164, s82, v172
	v_add_u32_e32 v165, s82, v176
	v_lshlrev_b32_e32 v172, 1, v178
	v_mfma_f32_32x32x16_bf16 v[16:31], v[194:197], v[190:193], v[16:31]
	v_lshrrev_b32_e32 v194, 3, v187
	ds_read_b64_tr_b16 v[188:189], v160
	ds_read_b64_tr_b16 v[190:191], v160 offset:2304
	ds_read_b64_tr_b16 v[242:243], v161
	ds_read_b64_tr_b16 v[244:245], v161 offset:2304
	v_add_u32_e32 v160, s81, v169
	ds_read_b64_tr_b16 v[246:247], v160
	ds_read_b64_tr_b16 v[248:249], v160 offset:2304
	ds_read_b64_tr_b16 v[160:161], v162
	ds_read_b64_tr_b16 v[162:163], v162 offset:2304
	ds_read_b128 v[250:253], v164
	ds_read_b128 v[164:167], v165
	s_waitcnt vmcnt(5)
	ds_write_b128 v177, v[136:139]
	ds_write_b128 v177, v[128:131] offset:9216
	ds_write_b128 v177, v[132:135] offset:18432
	s_waitcnt vmcnt(3)
	ds_write_b128 v177, v[144:147] offset:27648
	ds_write_b128 v171, v[140:143] offset:36864
	s_waitcnt vmcnt(2)
	ds_write_b128 v171, v[148:151] offset:46080
	s_waitcnt vmcnt(1)
	ds_write_b128 v171, v[152:155] offset:55296
	s_waitcnt vmcnt(0)
	ds_write_b128 v171, v[156:159] offset:64512
	s_waitcnt lgkmcnt(14)
	v_mfma_f32_32x32x16_bf16 v[96:111], v[180:183], v[210:213], v[96:111]
	s_waitcnt lgkmcnt(0)
	s_barrier
	v_or_b32_e32 v176, s0, v178
	v_ashrrev_i32_e32 v177, 31, v176
	v_lshl_add_u32 v195, v178, 2, s21
	v_mul_u32_u24_e32 v178, 0x440, v186
	v_mfma_f32_32x32x16_bf16 v[112:127], v[180:183], v[214:217], v[112:127]
	v_or_b32_e32 v180, s1, v194
	v_ashrrev_i32_e32 v181, 31, v180
	v_or_b32_e32 v130, 8, v180
	s_ashr_i32 s1, s0, 31
	v_lshlrev_b64 v[128:129], 11, v[180:181]
	v_ashrrev_i32_e32 v131, 31, v130
	v_lshl_add_u64 v[128:129], s[6:7], 0, v[128:129]
	s_lshl_b64 s[18:19], s[0:1], 1
	v_lshlrev_b64 v[130:131], 11, v[130:131]
	v_lshl_add_u64 v[128:129], v[128:129], 0, s[18:19]
	v_lshl_add_u64 v[130:131], s[6:7], 0, v[130:131]
	v_lshl_add_u64 v[128:129], v[128:129], 0, v[172:173]
	v_lshl_add_u64 v[130:131], v[130:131], 0, s[18:19]
	v_mfma_f32_32x32x16_bf16 v[64:79], v[198:201], v[210:213], v[64:79]
	v_lshl_add_u64 v[130:131], v[130:131], 0, v[172:173]
	s_ashr_i32 s0, s14, 12
	s_mulk_i32 s0, 0xc00
	s_ashr_i32 s1, s0, 31
	s_lshl_b64 s[0:1], s[0:1], 2
	s_add_u32 s0, s78, s0
	s_addc_u32 s1, s79, s1
	v_mfma_f32_32x32x16_bf16 v[80:95], v[198:201], v[214:217], v[80:95]
	global_load_dwordx4 v[196:199], v[128:129], off nt
	global_load_dwordx4 v[168:171], v[130:131], off nt
	v_or_b32_e32 v128, 16, v180
	v_ashrrev_i32_e32 v129, 31, v128
	v_or_b32_e32 v130, 24, v180
	v_lshlrev_b64 v[128:129], 11, v[128:129]
	v_ashrrev_i32_e32 v131, 31, v130
	v_lshl_add_u64 v[128:129], s[6:7], 0, v[128:129]
	v_lshlrev_b64 v[130:131], 11, v[130:131]
	v_lshl_add_u64 v[128:129], v[128:129], 0, s[18:19]
	v_lshl_add_u64 v[130:131], s[6:7], 0, v[130:131]
	v_lshl_add_u64 v[128:129], v[128:129], 0, v[172:173]
	v_lshl_add_u64 v[130:131], v[130:131], 0, s[18:19]
	v_lshl_add_u64 v[130:131], v[130:131], 0, v[172:173]
	global_load_dwordx4 v[156:159], v[128:129], off nt
	global_load_dwordx4 v[152:155], v[130:131], off nt
	v_lshl_add_u64 v[128:129], v[176:177], 2, s[0:1]
	v_lshl_add_u64 v[130:131], v[128:129], 0, s[12:13]
	v_add_co_u32_e32 v128, vcc, s83, v128
	v_or_b32_e32 v136, 32, v180
	s_nop 0
	v_addc_co_u32_e32 v129, vcc, 0, v129, vcc
	global_load_dwordx4 v[132:135], v[128:129], off
	s_nop 0
	global_load_dwordx4 v[128:131], v[130:131], off offset:16
	v_or_b32_e32 v138, 40, v180
	v_ashrrev_i32_e32 v137, 31, v136
	v_ashrrev_i32_e32 v139, 31, v138
	v_lshlrev_b64 v[136:137], 11, v[136:137]
	v_lshlrev_b64 v[138:139], 11, v[138:139]
	v_lshl_add_u64 v[136:137], s[6:7], 0, v[136:137]
	v_lshl_add_u64 v[138:139], s[6:7], 0, v[138:139]
	v_lshl_add_u64 v[136:137], v[136:137], 0, s[18:19]
	v_lshl_add_u64 v[138:139], v[138:139], 0, s[18:19]
	v_lshl_add_u64 v[136:137], v[136:137], 0, v[172:173]
	v_lshl_add_u64 v[138:139], v[138:139], 0, v[172:173]
	global_load_dwordx4 v[148:151], v[136:137], off nt
	global_load_dwordx4 v[144:147], v[138:139], off nt
	v_or_b32_e32 v136, 48, v180
	v_or_b32_e32 v138, 56, v180
	v_ashrrev_i32_e32 v137, 31, v136
	v_ashrrev_i32_e32 v139, 31, v138
	v_lshlrev_b64 v[136:137], 11, v[136:137]
	v_lshlrev_b64 v[138:139], 11, v[138:139]
	v_lshl_add_u64 v[136:137], s[6:7], 0, v[136:137]
	v_lshl_add_u64 v[138:139], s[6:7], 0, v[138:139]
	v_lshl_add_u64 v[136:137], v[136:137], 0, s[18:19]
	v_lshl_add_u64 v[138:139], v[138:139], 0, s[18:19]
	v_lshl_add_u64 v[136:137], v[136:137], 0, v[172:173]
	v_lshl_add_u64 v[138:139], v[138:139], 0, v[172:173]
	global_load_dwordx4 v[140:143], v[136:137], off nt
	s_nop 0
	global_load_dwordx4 v[136:139], v[138:139], off nt
	v_mfma_f32_32x32x16_bf16 v[96:111], v[218:221], v[234:237], v[96:111]
	v_add3_u32 v186, s21, v175, v178
	v_add_u32_e32 v187, 0x800, v186
	v_add_u32_e32 v192, 0x1a00, v186
	v_add_u32_e32 v193, 0x1c00, v186
	v_or_b32_e32 v181, s20, v194
	v_cmp_eq_u32_e32 vcc, 0, v185
	v_mfma_f32_32x32x16_bf16 v[112:127], v[218:221], v[238:241], v[112:127]
	v_mfma_f32_32x32x16_bf16 v[96:111], v[188:191], v[250:253], v[96:111]
	v_mfma_f32_32x32x16_bf16 v[112:127], v[188:191], v[164:167], v[112:127]
	s_nop 11
	ds_write2_b32 v186, v96, v112 offset1:32
	ds_write2_b32 v186, v97, v113 offset0:68 offset1:100
	ds_write2_b32 v186, v98, v114 offset0:136 offset1:168
	ds_write2_b32 v186, v99, v115 offset0:204 offset1:236
	v_add_u32_e32 v189, 0xa00, v186
	v_add_u32_e32 v188, 0x1000, v186
	v_and_b32_e32 v97, 64, v184
	ds_write2_b32 v187, v100, v116 offset0:32 offset1:64
	ds_write2_b32 v187, v101, v117 offset0:100 offset1:132
	ds_write2_b32 v187, v102, v118 offset0:168 offset1:200
	ds_write2_b32 v189, v103, v119 offset0:108 offset1:140
	ds_write2_b32 v188, v104, v120 offset0:64 offset1:96
	ds_write2_b32 v188, v105, v121 offset0:132 offset1:164
	ds_write2_b32 v188, v106, v122 offset0:200 offset1:232
	v_add_u32_e32 v190, 0x1400, v186
	v_add_u32_e32 v191, 0x1800, v186
	v_xor_b32_e32 v96, 1, v184
	v_add_u32_e32 v106, 64, v97
	ds_write2_b32 v190, v107, v123 offset0:12 offset1:44
	ds_write2_b32 v191, v108, v124 offset0:96 offset1:128
	ds_write2_b32 v191, v109, v125 offset0:164 offset1:196
	ds_write2_b32 v192, v110, v126 offset0:104 offset1:136
	ds_write2_b32 v193, v111, v127 offset0:44 offset1:76
	v_cmp_lt_i32_e64 s[0:1], v96, v106
	s_waitcnt lgkmcnt(0)
	v_mad_u32_u24 v100, v194, s84, v195
	s_waitcnt vmcnt(9)
	v_lshlrev_b32_e32 v104, 16, v196
	v_cndmask_b32_e64 v96, v184, v96, s[0:1]
	v_lshlrev_b32_e32 v175, 2, v96
	ds_read_b128 v[96:99], v100
	ds_read_b128 v[100:103], v100 offset:16
	v_and_b32_e32 v105, 0xffff0000, v196
	v_mfma_f32_32x32x16_bf16 v[32:47], v[202:205], v[210:213], v[32:47]
	v_xor_b32_e32 v107, 2, v184
	s_waitcnt vmcnt(5) lgkmcnt(1)
	v_fma_f32 v112, v132, v96, v104
	v_fma_f32 v113, v133, v97, v105
	v_lshlrev_b32_e32 v96, 16, v197
	v_and_b32_e32 v97, 0xffff0000, v197
	v_pk_fma_f32 v[114:115], v[134:135], v[98:99], v[96:97]
	v_lshlrev_b32_e32 v96, 16, v198
	v_and_b32_e32 v97, 0xffff0000, v198
	v_mfma_f32_32x32x16_bf16 v[48:63], v[202:205], v[214:217], v[48:63]
	s_waitcnt vmcnt(4) lgkmcnt(0)
	v_fma_f32 v116, v128, v100, v96
	v_fma_f32 v117, v129, v101, v97
	v_lshlrev_b32_e32 v96, 16, v199
	v_and_b32_e32 v97, 0xffff0000, v199
	v_pk_fma_f32 v[118:119], v[130:131], v[102:103], v[96:97]
	v_pk_mul_f32 v[96:97], v[112:113], v[112:113]
	v_pk_mul_f32 v[100:101], v[116:117], v[116:117]
	v_pk_mul_f32 v[98:99], v[114:115], v[114:115]
	v_mfma_f32_32x32x16_bf16 v[0:15], v[206:209], v[210:213], v[0:15]
	v_mul_f32_e64 v102, v118, v118
	v_mul_f32_e64 v103, v119, v119
	v_add_f32_e32 v96, v96, v97
	v_add_f32_e32 v97, v100, v101
	v_add_f32_e32 v96, v98, v96
	v_add_f32_e32 v97, v102, v97
	v_add_f32_e32 v96, v99, v96
	v_add_f32_e32 v97, v103, v97
	v_mfma_f32_32x32x16_bf16 v[16:31], v[206:209], v[214:217], v[16:31]
	v_add_f32_e32 v96, v96, v97
	ds_bpermute_b32 v97, v175, v96
	v_cmp_lt_i32_e64 s[0:1], v107, v106
	s_waitcnt lgkmcnt(0)
	v_add_f32_e32 v96, v96, v97
	v_mfma_f32_32x32x16_bf16 v[64:79], v[222:225], v[234:237], v[64:79]
	v_cndmask_b32_e64 v98, v184, v107, s[0:1]
	v_lshlrev_b32_e32 v178, 2, v98
	ds_bpermute_b32 v97, v178, v96
	v_xor_b32_e32 v98, 4, v184
	v_cmp_lt_i32_e64 s[0:1], v98, v106
	s_waitcnt lgkmcnt(0)
	v_add_f32_e32 v96, v96, v97
	v_mfma_f32_32x32x16_bf16 v[80:95], v[222:225], v[238:241], v[80:95]
	v_cndmask_b32_e64 v98, v184, v98, s[0:1]
	v_lshlrev_b32_e32 v183, 2, v98
	ds_bpermute_b32 v97, v183, v96
	s_lshl_b32 s0, s15, 2
	s_add_i32 s15, s0, 0
	s_add_i32 s15, s15, 0x24000
	v_lshl_add_u32 v182, v181, 4, s15
	v_mfma_f32_32x32x16_bf16 v[32:47], v[226:229], v[234:237], v[32:47]
	v_mfma_f32_32x32x16_bf16 v[48:63], v[226:229], v[238:241], v[48:63]
	v_mfma_f32_32x32x16_bf16 v[0:15], v[230:233], v[234:237], v[0:15]
	v_mfma_f32_32x32x16_bf16 v[16:31], v[230:233], v[238:241], v[16:31]
	v_mfma_f32_32x32x16_bf16 v[64:79], v[242:245], v[250:253], v[64:79]
	v_mfma_f32_32x32x16_bf16 v[80:95], v[242:245], v[164:167], v[80:95]
	v_mfma_f32_32x32x16_bf16 v[32:47], v[246:249], v[250:253], v[32:47]
	v_mfma_f32_32x32x16_bf16 v[48:63], v[246:249], v[164:167], v[48:63]
	v_mfma_f32_32x32x16_bf16 v[0:15], v[160:163], v[250:253], v[0:15]
	v_mfma_f32_32x32x16_bf16 v[16:31], v[160:163], v[164:167], v[16:31]
	s_and_saveexec_b64 s[0:1], vcc
	s_cbranch_execz .LBB0_1892
	s_waitcnt lgkmcnt(0)
	v_add_f32_e32 v96, v96, v97
	ds_write_b32 v182, v96

.LBB0_1898:
	s_or_b64 exec, exec, s[0:1]
	v_or_b32_e32 v96, 64, v180
	v_or_b32_e32 v98, 0x48, v180
	s_waitcnt lgkmcnt(0)
	v_ashrrev_i32_e32 v97, 31, v96
	v_ashrrev_i32_e32 v99, 31, v98
	v_lshlrev_b64 v[96:97], 11, v[96:97]
	v_lshlrev_b64 v[98:99], 11, v[98:99]
	v_lshl_add_u64 v[96:97], s[6:7], 0, v[96:97]
	v_lshl_add_u64 v[98:99], s[6:7], 0, v[98:99]
	v_lshl_add_u64 v[96:97], v[96:97], 0, s[18:19]
	v_lshl_add_u64 v[98:99], v[98:99], 0, s[18:19]
	s_waitcnt lgkmcnt(0)
	v_lshl_add_u64 v[96:97], v[96:97], 0, v[172:173]
	v_lshl_add_u64 v[98:99], v[98:99], 0, v[172:173]
	global_load_dwordx4 v[108:111], v[96:97], off nt
	global_load_dwordx4 v[104:107], v[98:99], off nt
	v_or_b32_e32 v96, 0x50, v180
	v_or_b32_e32 v98, 0x58, v180
	v_ashrrev_i32_e32 v97, 31, v96
	v_ashrrev_i32_e32 v99, 31, v98
	v_lshlrev_b64 v[96:97], 11, v[96:97]
	v_lshlrev_b64 v[98:99], 11, v[98:99]
	v_lshl_add_u64 v[96:97], s[6:7], 0, v[96:97]
	v_lshl_add_u64 v[98:99], s[6:7], 0, v[98:99]
	v_lshl_add_u64 v[96:97], v[96:97], 0, s[18:19]
	v_lshl_add_u64 v[98:99], v[98:99], 0, s[18:19]
	v_lshl_add_u64 v[96:97], v[96:97], 0, v[172:173]
	v_lshl_add_u64 v[98:99], v[98:99], 0, v[172:173]
	global_load_dwordx4 v[100:103], v[96:97], off nt
	s_nop 0
	global_load_dwordx4 v[96:99], v[98:99], off nt
	ds_write2_b32 v186, v64, v80 offset1:32
	ds_write2_b32 v186, v65, v81 offset0:68 offset1:100
	ds_write2_b32 v186, v66, v82 offset0:136 offset1:168
	ds_write2_b32 v186, v67, v83 offset0:204 offset1:236
	ds_write2_b32 v187, v68, v84 offset0:32 offset1:64
	ds_write2_b32 v187, v69, v85 offset0:100 offset1:132
	ds_write2_b32 v187, v70, v86 offset0:168 offset1:200
	ds_write2_b32 v189, v71, v87 offset0:108 offset1:140
	ds_write2_b32 v188, v72, v88 offset0:64 offset1:96
	ds_write2_b32 v188, v73, v89 offset0:132 offset1:164
	ds_write2_b32 v188, v74, v90 offset0:200 offset1:232
	ds_write2_b32 v190, v75, v91 offset0:12 offset1:44
	ds_write2_b32 v191, v76, v92 offset0:96 offset1:128
	ds_write2_b32 v191, v77, v93 offset0:164 offset1:196
	ds_write2_b32 v192, v78, v94 offset0:104 offset1:136
	ds_write2_b32 v193, v79, v95 offset0:44 offset1:76
	s_waitcnt lgkmcnt(0)
	ds_read_b128 v[64:67], v185
	ds_read_b128 v[68:71], v185 offset:16
	s_waitcnt vmcnt(7)
	v_lshlrev_b32_e32 v72, 16, v148
	v_and_b32_e32 v73, 0xffff0000, v148
	v_or_b32_e32 v168, 32, v181
	s_waitcnt lgkmcnt(1)
	v_pk_fma_f32 v[80:81], v[132:133], v[64:65], v[72:73]
	v_lshlrev_b32_e32 v64, 16, v149
	v_and_b32_e32 v65, 0xffff0000, v149
	v_pk_fma_f32 v[82:83], v[134:135], v[66:67], v[64:65]
	v_lshlrev_b32_e32 v64, 16, v150
	v_and_b32_e32 v65, 0xffff0000, v150
	s_waitcnt lgkmcnt(0)
	v_pk_fma_f32 v[84:85], v[128:129], v[68:69], v[64:65]
	v_lshlrev_b32_e32 v64, 16, v151
	v_and_b32_e32 v65, 0xffff0000, v151
	v_pk_fma_f32 v[86:87], v[130:131], v[70:71], v[64:65]
	v_pk_mul_f32 v[64:65], v[80:81], v[80:81]
	v_pk_mul_f32 v[68:69], v[84:85], v[84:85]
	v_pk_mul_f32 v[66:67], v[82:83], v[82:83]
	v_pk_mul_f32 v[70:71], v[86:87], v[86:87]
	v_add_f32_e32 v68, v68, v69
	v_add_f32_e32 v64, v64, v65
	v_add_f32_e32 v68, v70, v68
	v_add_f32_e32 v64, v66, v64
	v_add_f32_e32 v68, v71, v68
	v_add_f32_e32 v64, v67, v64
	v_add_f32_e32 v64, v64, v68
	ds_bpermute_b32 v65, v175, v64
	s_waitcnt lgkmcnt(0)
	v_add_f32_e32 v64, v64, v65
	ds_bpermute_b32 v65, v178, v64
	s_waitcnt lgkmcnt(0)
	v_add_f32_e32 v64, v64, v65
	ds_bpermute_b32 v65, v183, v64
	s_and_saveexec_b64 s[0:1], vcc
	s_cbranch_execz .LBB0_1900
	v_lshl_add_u32 v66, v168, 4, s15
	s_waitcnt lgkmcnt(0)
	v_add_f32_e32 v64, v64, v65
	ds_write_b32 v66, v64

.LBB0_1906:
	s_or_b64 exec, exec, s[0:1]
	v_or_b32_e32 v64, 0x60, v180
	v_or_b32_e32 v66, 0x68, v180
	s_waitcnt lgkmcnt(0)
	v_ashrrev_i32_e32 v65, 31, v64
	v_ashrrev_i32_e32 v67, 31, v66
	v_lshlrev_b64 v[64:65], 11, v[64:65]
	v_lshlrev_b64 v[66:67], 11, v[66:67]
	v_lshl_add_u64 v[64:65], s[6:7], 0, v[64:65]
	v_lshl_add_u64 v[66:67], s[6:7], 0, v[66:67]
	v_lshl_add_u64 v[64:65], v[64:65], 0, s[18:19]
	v_lshl_add_u64 v[66:67], v[66:67], 0, s[18:19]
	s_waitcnt lgkmcnt(0)
	v_lshl_add_u64 v[64:65], v[64:65], 0, v[172:173]
	v_lshl_add_u64 v[66:67], v[66:67], 0, v[172:173]
	global_load_dwordx4 v[76:79], v[64:65], off nt
	global_load_dwordx4 v[72:75], v[66:67], off nt
	v_or_b32_e32 v64, 0x70, v180
	v_or_b32_e32 v66, 0x78, v180
	v_ashrrev_i32_e32 v65, 31, v64
	v_ashrrev_i32_e32 v67, 31, v66
	v_lshlrev_b64 v[64:65], 11, v[64:65]
	v_lshlrev_b64 v[66:67], 11, v[66:67]
	v_lshl_add_u64 v[64:65], s[6:7], 0, v[64:65]
	v_lshl_add_u64 v[66:67], s[6:7], 0, v[66:67]
	v_lshl_add_u64 v[64:65], v[64:65], 0, s[18:19]
	v_lshl_add_u64 v[66:67], v[66:67], 0, s[18:19]
	v_lshl_add_u64 v[64:65], v[64:65], 0, v[172:173]
	v_lshl_add_u64 v[66:67], v[66:67], 0, v[172:173]
	global_load_dwordx4 v[68:71], v[64:65], off nt
	s_nop 0
	global_load_dwordx4 v[64:67], v[66:67], off nt
	ds_write2_b32 v186, v32, v48 offset1:32
	ds_write2_b32 v186, v33, v49 offset0:68 offset1:100
	ds_write2_b32 v186, v34, v50 offset0:136 offset1:168
	ds_write2_b32 v186, v35, v51 offset0:204 offset1:236
	ds_write2_b32 v187, v36, v52 offset0:32 offset1:64
	ds_write2_b32 v187, v37, v53 offset0:100 offset1:132
	ds_write2_b32 v187, v38, v54 offset0:168 offset1:200
	ds_write2_b32 v189, v39, v55 offset0:108 offset1:140
	ds_write2_b32 v188, v40, v56 offset0:64 offset1:96
	ds_write2_b32 v188, v41, v57 offset0:132 offset1:164
	ds_write2_b32 v188, v42, v58 offset0:200 offset1:232
	ds_write2_b32 v190, v43, v59 offset0:12 offset1:44
	ds_write2_b32 v191, v44, v60 offset0:96 offset1:128
	ds_write2_b32 v191, v45, v61 offset0:164 offset1:196
	ds_write2_b32 v192, v46, v62 offset0:104 offset1:136
	ds_write2_b32 v193, v47, v63 offset0:44 offset1:76
	s_waitcnt lgkmcnt(0)
	ds_read_b128 v[32:35], v185
	ds_read_b128 v[36:39], v185 offset:16
	s_waitcnt vmcnt(7)
	v_lshlrev_b32_e32 v40, 16, v108
	v_and_b32_e32 v41, 0xffff0000, v108
	v_or_b32_e32 v108, 64, v181
	s_waitcnt lgkmcnt(1)
	v_pk_fma_f32 v[32:33], v[132:133], v[32:33], v[40:41]
	v_lshlrev_b32_e32 v40, 16, v109
	v_and_b32_e32 v41, 0xffff0000, v109
	v_pk_fma_f32 v[34:35], v[134:135], v[34:35], v[40:41]
	v_lshlrev_b32_e32 v40, 16, v110
	v_and_b32_e32 v41, 0xffff0000, v110
	s_waitcnt lgkmcnt(0)
	v_pk_fma_f32 v[36:37], v[128:129], v[36:37], v[40:41]
	v_lshlrev_b32_e32 v40, 16, v111
	v_and_b32_e32 v41, 0xffff0000, v111
	v_pk_fma_f32 v[38:39], v[130:131], v[38:39], v[40:41]
	v_pk_mul_f32 v[40:41], v[32:33], v[32:33]
	v_pk_mul_f32 v[44:45], v[36:37], v[36:37]
	v_pk_mul_f32 v[42:43], v[34:35], v[34:35]
	v_pk_mul_f32 v[46:47], v[38:39], v[38:39]
	v_add_f32_e32 v44, v44, v45
	v_add_f32_e32 v40, v40, v41
	v_add_f32_e32 v44, v46, v44
	v_add_f32_e32 v40, v42, v40
	v_add_f32_e32 v44, v47, v44
	v_add_f32_e32 v40, v43, v40
	v_add_f32_e32 v40, v40, v44
	ds_bpermute_b32 v41, v175, v40
	s_waitcnt lgkmcnt(0)
	v_add_f32_e32 v40, v40, v41
	ds_bpermute_b32 v41, v178, v40
	s_waitcnt lgkmcnt(0)
	v_add_f32_e32 v40, v40, v41
	ds_bpermute_b32 v41, v183, v40
	s_and_saveexec_b64 s[0:1], vcc
	s_cbranch_execz .LBB0_1908
	v_lshl_add_u32 v42, v108, 4, s15
	s_waitcnt lgkmcnt(0)
	v_add_f32_e32 v40, v40, v41
	ds_write_b32 v42, v40
